# SwiGLU epilogues: -log2e and -ln2 folded into the per-row scale and per-column bias (one multiply less per gate value)
# baseline (speedup 1.0000x reference)
.LBB0_780:
	v_lshl_or_b32 v224, s0, 7, v181
	v_lshl_add_u32 v223, v1, 2, s1
	ds_read_b32 v206, v223
	ds_read_b32 v208, v223 offset:64
	ds_read_b32 v210, v223 offset:128
	ds_read_b32 v212, v223 offset:192
	ds_read_b32 v214, v223 offset:512
	ds_read_b32 v216, v223 offset:576
	ds_read_b32 v218, v223 offset:640
	ds_read_b32 v220, v223 offset:704
	s_lshl_b32 s12, s49, 2
	s_add_i32 s12, s1, s12
	v_lshl_add_u32 v222, v172, 2, s12
	s_lshl_b32 s11, s10, 8
	ds_read_b128 v[62:65], v222 offset:1024
	ds_read_b128 v[58:61], v222 offset:1040
	ds_read_b128 v[54:57], v222 offset:1536
	ds_read_b128 v[50:53], v222 offset:1552
	v_ashrrev_i32_e32 v225, 31, v224
	v_lshlrev_b64 v[224:225], 1, v[224:225]
	v_lshl_add_u64 v[224:225], s[20:21], 0, v[224:225]
	s_waitcnt lgkmcnt(4)
	v_fmamk_f32 v206, v206, 0x3a800000, v185
	v_fmamk_f32 v208, v208, 0x3a800000, v185
	v_fmamk_f32 v210, v210, 0x3a800000, v185
	v_fmamk_f32 v212, v212, 0x3a800000, v185
	v_fmamk_f32 v214, v214, 0x3a800000, v185
	v_fmamk_f32 v216, v216, 0x3a800000, v185
	v_fmamk_f32 v218, v218, 0x3a800000, v185
	v_fmamk_f32 v220, v220, 0x3a800000, v185
	v_rsq_f32_e32 v206, v206
	v_rsq_f32_e32 v208, v208
	v_rsq_f32_e32 v210, v210
	v_rsq_f32_e32 v212, v212
	v_rsq_f32_e32 v214, v214
	v_rsq_f32_e32 v216, v216
	v_rsq_f32_e32 v218, v218
	v_rsq_f32_e32 v220, v220
	s_waitcnt lgkmcnt(0)
	v_mul_f32_e32 v62, 0xbfb8aa3b, v62
	v_mul_f32_e32 v58, 0xbfb8aa3b, v58
	v_mul_f32_e32 v63, 0xbfb8aa3b, v63
	v_mul_f32_e32 v59, 0xbfb8aa3b, v59
	v_mul_f32_e32 v64, 0xbfb8aa3b, v64
	v_mul_f32_e32 v60, 0xbfb8aa3b, v60
	v_mul_f32_e32 v65, 0xbfb8aa3b, v65
	v_mul_f32_e32 v61, 0xbfb8aa3b, v61
	v_mul_f32_e32 v54, 0xbf317218, v54
	v_mul_f32_e32 v50, 0xbf317218, v50
	v_mul_f32_e32 v55, 0xbf317218, v55
	v_mul_f32_e32 v51, 0xbf317218, v51
	v_mul_f32_e32 v56, 0xbf317218, v56
	v_mul_f32_e32 v52, 0xbf317218, v52
	v_mul_f32_e32 v57, 0xbf317218, v57
	v_mul_f32_e32 v53, 0xbf317218, v53
	v_mul_f32_e32 v207, 0xbf317218, v206
	v_mul_f32_e32 v206, 0xbfb8aa3b, v206
	v_fma_f32 v142, v142, v206, v62
	v_fma_f32 v143, v143, v206, v63
	v_fma_f32 v144, v144, v206, v64
	v_fma_f32 v145, v145, v206, v65
	v_fma_f32 v138, v138, v206, v58
	v_fma_f32 v139, v139, v206, v59
	v_fma_f32 v140, v140, v206, v60
	v_fma_f32 v141, v141, v206, v61
	v_fma_f32 v134, v134, v207, v54
	v_fma_f32 v135, v135, v207, v55
	v_fma_f32 v136, v136, v207, v56
	v_fma_f32 v137, v137, v207, v57
	v_fma_f32 v130, v130, v207, v50
	v_fma_f32 v131, v131, v207, v51
	v_fma_f32 v132, v132, v207, v52
	v_fma_f32 v133, v133, v207, v53
	v_exp_f32_e32 v190, v142
	v_exp_f32_e32 v191, v143
	v_exp_f32_e32 v192, v144
	v_exp_f32_e32 v193, v145
	v_exp_f32_e32 v194, v138
	v_exp_f32_e32 v195, v139
	v_exp_f32_e32 v196, v140
	v_exp_f32_e32 v197, v141
	v_add_u32_e32 v226, s11, v1
	v_mad_i64_i32 v[226:227], s[12:13], v226, s90, v[224:225]
	v_add_f32_e32 v190, 1.0, v190
	v_add_f32_e32 v191, 1.0, v191
	v_add_f32_e32 v192, 1.0, v192
	v_add_f32_e32 v193, 1.0, v193
	v_add_f32_e32 v194, 1.0, v194
	v_add_f32_e32 v195, 1.0, v195
	v_add_f32_e32 v196, 1.0, v196
	v_add_f32_e32 v197, 1.0, v197
	v_rcp_f32_e32 v190, v190
	v_rcp_f32_e32 v191, v191
	v_rcp_f32_e32 v192, v192
	v_rcp_f32_e32 v193, v193
	v_rcp_f32_e32 v194, v194
	v_rcp_f32_e32 v195, v195
	v_rcp_f32_e32 v196, v196
	v_rcp_f32_e32 v197, v197
	v_mul_f32_e32 v142, v142, v190
	v_mul_f32_e32 v143, v143, v191
	v_mul_f32_e32 v144, v144, v192
	v_mul_f32_e32 v145, v145, v193
	v_mul_f32_e32 v138, v138, v194
	v_mul_f32_e32 v139, v139, v195
	v_mul_f32_e32 v140, v140, v196
	v_mul_f32_e32 v141, v141, v197
	v_mul_f32_e32 v142, v134, v142
	v_mul_f32_e32 v143, v135, v143
	v_mul_f32_e32 v144, v136, v144
	v_mul_f32_e32 v145, v137, v145
	v_mul_f32_e32 v138, v130, v138
	v_mul_f32_e32 v139, v131, v139
	v_mul_f32_e32 v140, v132, v140
	v_mul_f32_e32 v141, v133, v141
	v_cvt_pk_bf16_f32 v198, v142, v143
	v_cvt_pk_bf16_f32 v199, v144, v145
	v_cvt_pk_bf16_f32 v200, v138, v139
	v_cvt_pk_bf16_f32 v201, v140, v141
	global_store_dwordx4 v[226:227], v[198:201], off
	v_mul_f32_e32 v209, 0xbf317218, v208
	v_mul_f32_e32 v208, 0xbfb8aa3b, v208
	v_fma_f32 v126, v126, v208, v62
	v_fma_f32 v127, v127, v208, v63
	v_fma_f32 v128, v128, v208, v64
	v_fma_f32 v129, v129, v208, v65
	v_fma_f32 v122, v122, v208, v58
	v_fma_f32 v123, v123, v208, v59
	v_fma_f32 v124, v124, v208, v60
	v_fma_f32 v125, v125, v208, v61
	v_fma_f32 v118, v118, v209, v54
	v_fma_f32 v119, v119, v209, v55
	v_fma_f32 v120, v120, v209, v56
	v_fma_f32 v121, v121, v209, v57
	v_fma_f32 v114, v114, v209, v50
	v_fma_f32 v115, v115, v209, v51
	v_fma_f32 v116, v116, v209, v52
	v_fma_f32 v117, v117, v209, v53
	v_exp_f32_e32 v190, v126
	v_exp_f32_e32 v191, v127
	v_exp_f32_e32 v192, v128
	v_exp_f32_e32 v193, v129
	v_exp_f32_e32 v194, v122
	v_exp_f32_e32 v195, v123
	v_exp_f32_e32 v196, v124
	v_exp_f32_e32 v197, v125
	v_add_u32_e32 v228, s11, v174
	v_mad_i64_i32 v[228:229], s[12:13], v228, s90, v[224:225]
	v_add_f32_e32 v190, 1.0, v190
	v_add_f32_e32 v191, 1.0, v191
	v_add_f32_e32 v192, 1.0, v192
	v_add_f32_e32 v193, 1.0, v193
	v_add_f32_e32 v194, 1.0, v194
	v_add_f32_e32 v195, 1.0, v195
	v_add_f32_e32 v196, 1.0, v196
	v_add_f32_e32 v197, 1.0, v197
	v_rcp_f32_e32 v190, v190
	v_rcp_f32_e32 v191, v191
	v_rcp_f32_e32 v192, v192
	v_rcp_f32_e32 v193, v193
	v_rcp_f32_e32 v194, v194
	v_rcp_f32_e32 v195, v195
	v_rcp_f32_e32 v196, v196
	v_rcp_f32_e32 v197, v197
	v_mul_f32_e32 v126, v126, v190
	v_mul_f32_e32 v127, v127, v191
	v_mul_f32_e32 v128, v128, v192
	v_mul_f32_e32 v129, v129, v193
	v_mul_f32_e32 v122, v122, v194
	v_mul_f32_e32 v123, v123, v195
	v_mul_f32_e32 v124, v124, v196
	v_mul_f32_e32 v125, v125, v197
	v_mul_f32_e32 v126, v118, v126
	v_mul_f32_e32 v127, v119, v127
	v_mul_f32_e32 v128, v120, v128
	v_mul_f32_e32 v129, v121, v129
	v_mul_f32_e32 v122, v114, v122
	v_mul_f32_e32 v123, v115, v123
	v_mul_f32_e32 v124, v116, v124
	v_mul_f32_e32 v125, v117, v125
	v_cvt_pk_bf16_f32 v202, v126, v127
	v_cvt_pk_bf16_f32 v203, v128, v129
	v_cvt_pk_bf16_f32 v204, v122, v123
	v_cvt_pk_bf16_f32 v205, v124, v125
	global_store_dwordx4 v[228:229], v[202:205], off
	v_mul_f32_e32 v211, 0xbf317218, v210
	v_mul_f32_e32 v210, 0xbfb8aa3b, v210
	v_fma_f32 v110, v110, v210, v62
	v_fma_f32 v111, v111, v210, v63
	v_fma_f32 v112, v112, v210, v64
	v_fma_f32 v113, v113, v210, v65
	v_fma_f32 v106, v106, v210, v58
	v_fma_f32 v107, v107, v210, v59
	v_fma_f32 v108, v108, v210, v60
	v_fma_f32 v109, v109, v210, v61
	v_fma_f32 v102, v102, v211, v54
	v_fma_f32 v103, v103, v211, v55
	v_fma_f32 v104, v104, v211, v56
	v_fma_f32 v105, v105, v211, v57
	v_fma_f32 v98, v98, v211, v50
	v_fma_f32 v99, v99, v211, v51
	v_fma_f32 v100, v100, v211, v52
	v_fma_f32 v101, v101, v211, v53
	v_exp_f32_e32 v190, v110
	v_exp_f32_e32 v191, v111
	v_exp_f32_e32 v192, v112
	v_exp_f32_e32 v193, v113
	v_exp_f32_e32 v194, v106
	v_exp_f32_e32 v195, v107
	v_exp_f32_e32 v196, v108
	v_exp_f32_e32 v197, v109
	v_add_u32_e32 v226, s11, v175
	v_mad_i64_i32 v[226:227], s[12:13], v226, s90, v[224:225]
	v_add_f32_e32 v190, 1.0, v190
	v_add_f32_e32 v191, 1.0, v191
	v_add_f32_e32 v192, 1.0, v192
	v_add_f32_e32 v193, 1.0, v193
	v_add_f32_e32 v194, 1.0, v194
	v_add_f32_e32 v195, 1.0, v195
	v_add_f32_e32 v196, 1.0, v196
	v_add_f32_e32 v197, 1.0, v197
	v_rcp_f32_e32 v190, v190
	v_rcp_f32_e32 v191, v191
	v_rcp_f32_e32 v192, v192
	v_rcp_f32_e32 v193, v193
	v_rcp_f32_e32 v194, v194
	v_rcp_f32_e32 v195, v195
	v_rcp_f32_e32 v196, v196
	v_rcp_f32_e32 v197, v197
	v_mul_f32_e32 v110, v110, v190
	v_mul_f32_e32 v111, v111, v191
	v_mul_f32_e32 v112, v112, v192
	v_mul_f32_e32 v113, v113, v193
	v_mul_f32_e32 v106, v106, v194
	v_mul_f32_e32 v107, v107, v195
	v_mul_f32_e32 v108, v108, v196
	v_mul_f32_e32 v109, v109, v197
	v_mul_f32_e32 v110, v102, v110
	v_mul_f32_e32 v111, v103, v111
	v_mul_f32_e32 v112, v104, v112
	v_mul_f32_e32 v113, v105, v113
	v_mul_f32_e32 v106, v98, v106
	v_mul_f32_e32 v107, v99, v107
	v_mul_f32_e32 v108, v100, v108
	v_mul_f32_e32 v109, v101, v109
	v_cvt_pk_bf16_f32 v198, v110, v111
	v_cvt_pk_bf16_f32 v199, v112, v113
	v_cvt_pk_bf16_f32 v200, v106, v107
	v_cvt_pk_bf16_f32 v201, v108, v109
	global_store_dwordx4 v[226:227], v[198:201], off
	v_mul_f32_e32 v213, 0xbf317218, v212
	v_mul_f32_e32 v212, 0xbfb8aa3b, v212
	v_fma_f32 v94, v94, v212, v62
	v_fma_f32 v95, v95, v212, v63
	v_fma_f32 v96, v96, v212, v64
	v_fma_f32 v97, v97, v212, v65
	v_fma_f32 v90, v90, v212, v58
	v_fma_f32 v91, v91, v212, v59
	v_fma_f32 v92, v92, v212, v60
	v_fma_f32 v93, v93, v212, v61
	v_fma_f32 v86, v86, v213, v54
	v_fma_f32 v87, v87, v213, v55
	v_fma_f32 v88, v88, v213, v56
	v_fma_f32 v89, v89, v213, v57
	v_fma_f32 v82, v82, v213, v50
	v_fma_f32 v83, v83, v213, v51
	v_fma_f32 v84, v84, v213, v52
	v_fma_f32 v85, v85, v213, v53
	v_exp_f32_e32 v190, v94
	v_exp_f32_e32 v191, v95
	v_exp_f32_e32 v192, v96
	v_exp_f32_e32 v193, v97
	v_exp_f32_e32 v194, v90
	v_exp_f32_e32 v195, v91
	v_exp_f32_e32 v196, v92
	v_exp_f32_e32 v197, v93
	v_add_u32_e32 v228, s11, v176
	v_mad_i64_i32 v[228:229], s[12:13], v228, s90, v[224:225]
	v_add_f32_e32 v190, 1.0, v190
	v_add_f32_e32 v191, 1.0, v191
	v_add_f32_e32 v192, 1.0, v192
	v_add_f32_e32 v193, 1.0, v193
	v_add_f32_e32 v194, 1.0, v194
	v_add_f32_e32 v195, 1.0, v195
	v_add_f32_e32 v196, 1.0, v196
	v_add_f32_e32 v197, 1.0, v197
	v_rcp_f32_e32 v190, v190
	v_rcp_f32_e32 v191, v191
	v_rcp_f32_e32 v192, v192
	v_rcp_f32_e32 v193, v193
	v_rcp_f32_e32 v194, v194
	v_rcp_f32_e32 v195, v195
	v_rcp_f32_e32 v196, v196
	v_rcp_f32_e32 v197, v197
	v_mul_f32_e32 v94, v94, v190
	v_mul_f32_e32 v95, v95, v191
	v_mul_f32_e32 v96, v96, v192
	v_mul_f32_e32 v97, v97, v193
	v_mul_f32_e32 v90, v90, v194
	v_mul_f32_e32 v91, v91, v195
	v_mul_f32_e32 v92, v92, v196
	v_mul_f32_e32 v93, v93, v197
	v_mul_f32_e32 v94, v86, v94
	v_mul_f32_e32 v95, v87, v95
	v_mul_f32_e32 v96, v88, v96
	v_mul_f32_e32 v97, v89, v97
	v_mul_f32_e32 v90, v82, v90
	v_mul_f32_e32 v91, v83, v91
	v_mul_f32_e32 v92, v84, v92
	v_mul_f32_e32 v93, v85, v93
	v_cvt_pk_bf16_f32 v202, v94, v95
	v_cvt_pk_bf16_f32 v203, v96, v97
	v_cvt_pk_bf16_f32 v204, v90, v91
	v_cvt_pk_bf16_f32 v205, v92, v93
	global_store_dwordx4 v[228:229], v[202:205], off
	v_mul_f32_e32 v215, 0xbf317218, v214
	v_mul_f32_e32 v214, 0xbfb8aa3b, v214
	v_fma_f32 v78, v78, v214, v62
	v_fma_f32 v79, v79, v214, v63
	v_fma_f32 v80, v80, v214, v64
	v_fma_f32 v81, v81, v214, v65
	v_fma_f32 v74, v74, v214, v58
	v_fma_f32 v75, v75, v214, v59
	v_fma_f32 v76, v76, v214, v60
	v_fma_f32 v77, v77, v214, v61
	v_fma_f32 v70, v70, v215, v54
	v_fma_f32 v71, v71, v215, v55
	v_fma_f32 v72, v72, v215, v56
	v_fma_f32 v73, v73, v215, v57
	v_fma_f32 v66, v66, v215, v50
	v_fma_f32 v67, v67, v215, v51
	v_fma_f32 v68, v68, v215, v52
	v_fma_f32 v69, v69, v215, v53
	v_exp_f32_e32 v190, v78
	v_exp_f32_e32 v191, v79
	v_exp_f32_e32 v192, v80
	v_exp_f32_e32 v193, v81
	v_exp_f32_e32 v194, v74
	v_exp_f32_e32 v195, v75
	v_exp_f32_e32 v196, v76
	v_exp_f32_e32 v197, v77
	v_add_u32_e32 v226, s11, v177
	v_mad_i64_i32 v[226:227], s[12:13], v226, s90, v[224:225]
	v_add_f32_e32 v190, 1.0, v190
	v_add_f32_e32 v191, 1.0, v191
	v_add_f32_e32 v192, 1.0, v192
	v_add_f32_e32 v193, 1.0, v193
	v_add_f32_e32 v194, 1.0, v194
	v_add_f32_e32 v195, 1.0, v195
	v_add_f32_e32 v196, 1.0, v196
	v_add_f32_e32 v197, 1.0, v197
	v_rcp_f32_e32 v190, v190
	v_rcp_f32_e32 v191, v191
	v_rcp_f32_e32 v192, v192
	v_rcp_f32_e32 v193, v193
	v_rcp_f32_e32 v194, v194
	v_rcp_f32_e32 v195, v195
	v_rcp_f32_e32 v196, v196
	v_rcp_f32_e32 v197, v197
	v_mul_f32_e32 v78, v78, v190
	v_mul_f32_e32 v79, v79, v191
	v_mul_f32_e32 v80, v80, v192
	v_mul_f32_e32 v81, v81, v193
	v_mul_f32_e32 v74, v74, v194
	v_mul_f32_e32 v75, v75, v195
	v_mul_f32_e32 v76, v76, v196
	v_mul_f32_e32 v77, v77, v197
	v_mul_f32_e32 v78, v70, v78
	v_mul_f32_e32 v79, v71, v79
	v_mul_f32_e32 v80, v72, v80
	v_mul_f32_e32 v81, v73, v81
	v_mul_f32_e32 v74, v66, v74
	v_mul_f32_e32 v75, v67, v75
	v_mul_f32_e32 v76, v68, v76
	v_mul_f32_e32 v77, v69, v77
	v_cvt_pk_bf16_f32 v198, v78, v79
	v_cvt_pk_bf16_f32 v199, v80, v81
	v_cvt_pk_bf16_f32 v200, v74, v75
	v_cvt_pk_bf16_f32 v201, v76, v77
	global_store_dwordx4 v[226:227], v[198:201], off
	v_mul_f32_e32 v217, 0xbf317218, v216
	v_mul_f32_e32 v216, 0xbfb8aa3b, v216
	v_fma_f32 v46, v46, v216, v62
	v_fma_f32 v47, v47, v216, v63
	v_fma_f32 v48, v48, v216, v64
	v_fma_f32 v49, v49, v216, v65
	v_fma_f32 v42, v42, v216, v58
	v_fma_f32 v43, v43, v216, v59
	v_fma_f32 v44, v44, v216, v60
	v_fma_f32 v45, v45, v216, v61
	v_fma_f32 v38, v38, v217, v54
	v_fma_f32 v39, v39, v217, v55
	v_fma_f32 v40, v40, v217, v56
	v_fma_f32 v41, v41, v217, v57
	v_fma_f32 v34, v34, v217, v50
	v_fma_f32 v35, v35, v217, v51
	v_fma_f32 v36, v36, v217, v52
	v_fma_f32 v37, v37, v217, v53
	v_exp_f32_e32 v190, v46
	v_exp_f32_e32 v191, v47
	v_exp_f32_e32 v192, v48
	v_exp_f32_e32 v193, v49
	v_exp_f32_e32 v194, v42
	v_exp_f32_e32 v195, v43
	v_exp_f32_e32 v196, v44
	v_exp_f32_e32 v197, v45
	v_add_u32_e32 v228, s11, v178
	v_mad_i64_i32 v[228:229], s[12:13], v228, s90, v[224:225]
	v_add_f32_e32 v190, 1.0, v190
	v_add_f32_e32 v191, 1.0, v191
	v_add_f32_e32 v192, 1.0, v192
	v_add_f32_e32 v193, 1.0, v193
	v_add_f32_e32 v194, 1.0, v194
	v_add_f32_e32 v195, 1.0, v195
	v_add_f32_e32 v196, 1.0, v196
	v_add_f32_e32 v197, 1.0, v197
	v_rcp_f32_e32 v190, v190
	v_rcp_f32_e32 v191, v191
	v_rcp_f32_e32 v192, v192
	v_rcp_f32_e32 v193, v193
	v_rcp_f32_e32 v194, v194
	v_rcp_f32_e32 v195, v195
	v_rcp_f32_e32 v196, v196
	v_rcp_f32_e32 v197, v197
	v_mul_f32_e32 v46, v46, v190
	v_mul_f32_e32 v47, v47, v191
	v_mul_f32_e32 v48, v48, v192
	v_mul_f32_e32 v49, v49, v193
	v_mul_f32_e32 v42, v42, v194
	v_mul_f32_e32 v43, v43, v195
	v_mul_f32_e32 v44, v44, v196
	v_mul_f32_e32 v45, v45, v197
	v_mul_f32_e32 v46, v38, v46
	v_mul_f32_e32 v47, v39, v47
	v_mul_f32_e32 v48, v40, v48
	v_mul_f32_e32 v49, v41, v49
	v_mul_f32_e32 v42, v34, v42
	v_mul_f32_e32 v43, v35, v43
	v_mul_f32_e32 v44, v36, v44
	v_mul_f32_e32 v45, v37, v45
	v_cvt_pk_bf16_f32 v202, v46, v47
	v_cvt_pk_bf16_f32 v203, v48, v49
	v_cvt_pk_bf16_f32 v204, v42, v43
	v_cvt_pk_bf16_f32 v205, v44, v45
	global_store_dwordx4 v[228:229], v[202:205], off
	v_mul_f32_e32 v219, 0xbf317218, v218
	v_mul_f32_e32 v218, 0xbfb8aa3b, v218
	v_fma_f32 v30, v30, v218, v62
	v_fma_f32 v31, v31, v218, v63
	v_fma_f32 v32, v32, v218, v64
	v_fma_f32 v33, v33, v218, v65
	v_fma_f32 v26, v26, v218, v58
	v_fma_f32 v27, v27, v218, v59
	v_fma_f32 v28, v28, v218, v60
	v_fma_f32 v29, v29, v218, v61
	v_fma_f32 v22, v22, v219, v54
	v_fma_f32 v23, v23, v219, v55
	v_fma_f32 v24, v24, v219, v56
	v_fma_f32 v25, v25, v219, v57
	v_fma_f32 v18, v18, v219, v50
	v_fma_f32 v19, v19, v219, v51
	v_fma_f32 v20, v20, v219, v52
	v_fma_f32 v21, v21, v219, v53
	v_exp_f32_e32 v190, v30
	v_exp_f32_e32 v191, v31
	v_exp_f32_e32 v192, v32
	v_exp_f32_e32 v193, v33
	v_exp_f32_e32 v194, v26
	v_exp_f32_e32 v195, v27
	v_exp_f32_e32 v196, v28
	v_exp_f32_e32 v197, v29
	v_add_u32_e32 v226, s11, v179
	v_mad_i64_i32 v[226:227], s[12:13], v226, s90, v[224:225]
	v_add_f32_e32 v190, 1.0, v190
	v_add_f32_e32 v191, 1.0, v191
	v_add_f32_e32 v192, 1.0, v192
	v_add_f32_e32 v193, 1.0, v193
	v_add_f32_e32 v194, 1.0, v194
	v_add_f32_e32 v195, 1.0, v195
	v_add_f32_e32 v196, 1.0, v196
	v_add_f32_e32 v197, 1.0, v197
	v_rcp_f32_e32 v190, v190
	v_rcp_f32_e32 v191, v191
	v_rcp_f32_e32 v192, v192
	v_rcp_f32_e32 v193, v193
	v_rcp_f32_e32 v194, v194
	v_rcp_f32_e32 v195, v195
	v_rcp_f32_e32 v196, v196
	v_rcp_f32_e32 v197, v197
	v_mul_f32_e32 v30, v30, v190
	v_mul_f32_e32 v31, v31, v191
	v_mul_f32_e32 v32, v32, v192
	v_mul_f32_e32 v33, v33, v193
	v_mul_f32_e32 v26, v26, v194
	v_mul_f32_e32 v27, v27, v195
	v_mul_f32_e32 v28, v28, v196
	v_mul_f32_e32 v29, v29, v197
	v_mul_f32_e32 v30, v22, v30
	v_mul_f32_e32 v31, v23, v31
	v_mul_f32_e32 v32, v24, v32
	v_mul_f32_e32 v33, v25, v33
	v_mul_f32_e32 v26, v18, v26
	v_mul_f32_e32 v27, v19, v27
	v_mul_f32_e32 v28, v20, v28
	v_mul_f32_e32 v29, v21, v29
	v_cvt_pk_bf16_f32 v198, v30, v31
	v_cvt_pk_bf16_f32 v199, v32, v33
	v_cvt_pk_bf16_f32 v200, v26, v27
	v_cvt_pk_bf16_f32 v201, v28, v29
	global_store_dwordx4 v[226:227], v[198:201], off
	v_mul_f32_e32 v221, 0xbf317218, v220
	v_mul_f32_e32 v220, 0xbfb8aa3b, v220
	v_fma_f32 v14, v14, v220, v62
	v_fma_f32 v15, v15, v220, v63
	v_fma_f32 v16, v16, v220, v64
	v_fma_f32 v17, v17, v220, v65
	v_fma_f32 v10, v10, v220, v58
	v_fma_f32 v11, v11, v220, v59
	v_fma_f32 v12, v12, v220, v60
	v_fma_f32 v13, v13, v220, v61
	v_fma_f32 v6, v6, v221, v54
	v_fma_f32 v7, v7, v221, v55
	v_fma_f32 v8, v8, v221, v56
	v_fma_f32 v9, v9, v221, v57
	v_fma_f32 v2, v2, v221, v50
	v_fma_f32 v3, v3, v221, v51
	v_fma_f32 v4, v4, v221, v52
	v_fma_f32 v5, v5, v221, v53
	v_exp_f32_e32 v190, v14
	v_exp_f32_e32 v191, v15
	v_exp_f32_e32 v192, v16
	v_exp_f32_e32 v193, v17
	v_exp_f32_e32 v194, v10
	v_exp_f32_e32 v195, v11
	v_exp_f32_e32 v196, v12
	v_exp_f32_e32 v197, v13
	v_add_u32_e32 v228, s11, v180
	v_mad_i64_i32 v[228:229], s[12:13], v228, s90, v[224:225]
	v_add_f32_e32 v190, 1.0, v190
	v_add_f32_e32 v191, 1.0, v191
	v_add_f32_e32 v192, 1.0, v192
	v_add_f32_e32 v193, 1.0, v193
	v_add_f32_e32 v194, 1.0, v194
	v_add_f32_e32 v195, 1.0, v195
	v_add_f32_e32 v196, 1.0, v196
	v_add_f32_e32 v197, 1.0, v197
	v_rcp_f32_e32 v190, v190
	v_rcp_f32_e32 v191, v191
	v_rcp_f32_e32 v192, v192
	v_rcp_f32_e32 v193, v193
	v_rcp_f32_e32 v194, v194
	v_rcp_f32_e32 v195, v195
	v_rcp_f32_e32 v196, v196
	v_rcp_f32_e32 v197, v197
	v_mul_f32_e32 v14, v14, v190
	v_mul_f32_e32 v15, v15, v191
	v_mul_f32_e32 v16, v16, v192
	v_mul_f32_e32 v17, v17, v193
	v_mul_f32_e32 v10, v10, v194
	v_mul_f32_e32 v11, v11, v195
	v_mul_f32_e32 v12, v12, v196
	v_mul_f32_e32 v13, v13, v197
	v_mul_f32_e32 v14, v6, v14
	v_mul_f32_e32 v15, v7, v15
	v_mul_f32_e32 v16, v8, v16
	v_mul_f32_e32 v17, v9, v17
	v_mul_f32_e32 v10, v2, v10
	v_mul_f32_e32 v11, v3, v11
	v_mul_f32_e32 v12, v4, v12
	v_mul_f32_e32 v13, v5, v13
	v_cvt_pk_bf16_f32 v202, v14, v15
	v_cvt_pk_bf16_f32 v203, v16, v17
	v_cvt_pk_bf16_f32 v204, v10, v11
	v_cvt_pk_bf16_f32 v205, v12, v13
	global_store_dwordx4 v[228:229], v[202:205], off
	s_cmp_gt_i32 s10, 63
	s_cselect_b64 s[0:1], -1, 0
	s_and_b64 s[0:1], s[72:73], s[0:1]
	s_andn2_b64 vcc, exec, s[0:1]
	s_cbranch_vccnz .LBB0_785
	s_waitcnt vmcnt(0)
	s_barrier
	s_mov_b64 s[0:1], exec
	v_readlane_b32 s10, v250, 4
	v_readlane_b32 s11, v250, 5
	s_and_b64 s[10:11], s[0:1], s[10:11]
	s_mov_b64 exec, s[10:11]
	s_cbranch_execz .LBB0_784
	s_mov_b64 s[10:11], exec
	v_mbcnt_lo_u32_b32 v2, s10, 0
	buffer_wbl2 sc1
	s_waitcnt vmcnt(0)
	s_waitcnt vmcnt(0)
	v_mbcnt_hi_u32_b32 v2, s11, v2
	v_cmp_eq_u32_e32 vcc, 0, v2
	s_and_b64 s[12:13], exec, vcc
	s_mov_b64 exec, s[12:13]
	s_cbranch_execz .LBB0_784
	s_bcnt1_i32_b64 s3, s[10:11]
	v_mov_b32_e32 v2, s3
	global_atomic_add v151, v2, s[6:7] offset:2816

.LBB0_1482:
	v_lshl_or_b32 v224, s42, 7, v175
	v_lshl_add_u32 v223, v1, 2, s41
	ds_read_b32 v206, v223
	ds_read_b32 v208, v223 offset:64
	ds_read_b32 v210, v223 offset:128
	ds_read_b32 v212, v223 offset:192
	ds_read_b32 v214, v223 offset:512
	ds_read_b32 v216, v223 offset:576
	ds_read_b32 v218, v223 offset:640
	ds_read_b32 v220, v223 offset:704
	s_lshl_b32 s0, s57, 2
	s_add_i32 s0, s41, s0
	v_lshl_add_u32 v222, v166, 2, s0
	s_lshl_b32 s12, s40, 8
	ds_read_b128 v[110:113], v222 offset:1024
	ds_read_b128 v[106:109], v222 offset:1040
	ds_read_b128 v[102:105], v222 offset:1536
	ds_read_b128 v[98:101], v222 offset:1552
	v_ashrrev_i32_e32 v225, 31, v224
	v_lshlrev_b64 v[224:225], 1, v[224:225]
	v_lshl_add_u64 v[224:225], s[10:11], 0, v[224:225]
	s_waitcnt lgkmcnt(4)
	v_fmamk_f32 v206, v206, 0x3a800000, v179
	v_fmamk_f32 v208, v208, 0x3a800000, v179
	v_fmamk_f32 v210, v210, 0x3a800000, v179
	v_fmamk_f32 v212, v212, 0x3a800000, v179
	v_fmamk_f32 v214, v214, 0x3a800000, v179
	v_fmamk_f32 v216, v216, 0x3a800000, v179
	v_fmamk_f32 v218, v218, 0x3a800000, v179
	v_fmamk_f32 v220, v220, 0x3a800000, v179
	v_rsq_f32_e32 v206, v206
	v_rsq_f32_e32 v208, v208
	v_rsq_f32_e32 v210, v210
	v_rsq_f32_e32 v212, v212
	v_rsq_f32_e32 v214, v214
	v_rsq_f32_e32 v216, v216
	v_rsq_f32_e32 v218, v218
	v_rsq_f32_e32 v220, v220
	s_waitcnt lgkmcnt(0)
	v_mul_f32_e32 v110, 0xbfb8aa3b, v110
	v_mul_f32_e32 v106, 0xbfb8aa3b, v106
	v_mul_f32_e32 v111, 0xbfb8aa3b, v111
	v_mul_f32_e32 v107, 0xbfb8aa3b, v107
	v_mul_f32_e32 v112, 0xbfb8aa3b, v112
	v_mul_f32_e32 v108, 0xbfb8aa3b, v108
	v_mul_f32_e32 v113, 0xbfb8aa3b, v113
	v_mul_f32_e32 v109, 0xbfb8aa3b, v109
	v_mul_f32_e32 v102, 0xbf317218, v102
	v_mul_f32_e32 v98, 0xbf317218, v98
	v_mul_f32_e32 v103, 0xbf317218, v103
	v_mul_f32_e32 v99, 0xbf317218, v99
	v_mul_f32_e32 v104, 0xbf317218, v104
	v_mul_f32_e32 v100, 0xbf317218, v100
	v_mul_f32_e32 v105, 0xbf317218, v105
	v_mul_f32_e32 v101, 0xbf317218, v101
	v_mul_f32_e32 v207, 0xbf317218, v206
	v_mul_f32_e32 v206, 0xbfb8aa3b, v206
	v_fma_f32 v142, v142, v206, v110
	v_fma_f32 v143, v143, v206, v111
	v_fma_f32 v144, v144, v206, v112
	v_fma_f32 v145, v145, v206, v113
	v_fma_f32 v138, v138, v206, v106
	v_fma_f32 v139, v139, v206, v107
	v_fma_f32 v140, v140, v206, v108
	v_fma_f32 v141, v141, v206, v109
	v_fma_f32 v134, v134, v207, v102
	v_fma_f32 v135, v135, v207, v103
	v_fma_f32 v136, v136, v207, v104
	v_fma_f32 v137, v137, v207, v105
	v_fma_f32 v130, v130, v207, v98
	v_fma_f32 v131, v131, v207, v99
	v_fma_f32 v132, v132, v207, v100
	v_fma_f32 v133, v133, v207, v101
	v_exp_f32_e32 v190, v142
	v_exp_f32_e32 v191, v143
	v_exp_f32_e32 v192, v144
	v_exp_f32_e32 v193, v145
	v_exp_f32_e32 v194, v138
	v_exp_f32_e32 v195, v139
	v_exp_f32_e32 v196, v140
	v_exp_f32_e32 v197, v141
	v_add_u32_e32 v226, s12, v1
	v_mad_i64_i32 v[226:227], s[0:1], v226, s63, v[224:225]
	v_add_f32_e32 v190, 1.0, v190
	v_add_f32_e32 v191, 1.0, v191
	v_add_f32_e32 v192, 1.0, v192
	v_add_f32_e32 v193, 1.0, v193
	v_add_f32_e32 v194, 1.0, v194
	v_add_f32_e32 v195, 1.0, v195
	v_add_f32_e32 v196, 1.0, v196
	v_add_f32_e32 v197, 1.0, v197
	v_rcp_f32_e32 v190, v190
	v_rcp_f32_e32 v191, v191
	v_rcp_f32_e32 v192, v192
	v_rcp_f32_e32 v193, v193
	v_rcp_f32_e32 v194, v194
	v_rcp_f32_e32 v195, v195
	v_rcp_f32_e32 v196, v196
	v_rcp_f32_e32 v197, v197
	v_mul_f32_e32 v142, v142, v190
	v_mul_f32_e32 v143, v143, v191
	v_mul_f32_e32 v144, v144, v192
	v_mul_f32_e32 v145, v145, v193
	v_mul_f32_e32 v138, v138, v194
	v_mul_f32_e32 v139, v139, v195
	v_mul_f32_e32 v140, v140, v196
	v_mul_f32_e32 v141, v141, v197
	v_mul_f32_e32 v142, v134, v142
	v_mul_f32_e32 v143, v135, v143
	v_mul_f32_e32 v144, v136, v144
	v_mul_f32_e32 v145, v137, v145
	v_mul_f32_e32 v138, v130, v138
	v_mul_f32_e32 v139, v131, v139
	v_mul_f32_e32 v140, v132, v140
	v_mul_f32_e32 v141, v133, v141
	v_cvt_pk_bf16_f32 v198, v142, v143
	v_cvt_pk_bf16_f32 v199, v144, v145
	v_cvt_pk_bf16_f32 v200, v138, v139
	v_cvt_pk_bf16_f32 v201, v140, v141
	global_store_dwordx4 v[226:227], v[198:201], off
	v_mul_f32_e32 v209, 0xbf317218, v208
	v_mul_f32_e32 v208, 0xbfb8aa3b, v208
	v_fma_f32 v126, v126, v208, v110
	v_fma_f32 v127, v127, v208, v111
	v_fma_f32 v128, v128, v208, v112
	v_fma_f32 v129, v129, v208, v113
	v_fma_f32 v122, v122, v208, v106
	v_fma_f32 v123, v123, v208, v107
	v_fma_f32 v124, v124, v208, v108
	v_fma_f32 v125, v125, v208, v109
	v_fma_f32 v118, v118, v209, v102
	v_fma_f32 v119, v119, v209, v103
	v_fma_f32 v120, v120, v209, v104
	v_fma_f32 v121, v121, v209, v105
	v_fma_f32 v114, v114, v209, v98
	v_fma_f32 v115, v115, v209, v99
	v_fma_f32 v116, v116, v209, v100
	v_fma_f32 v117, v117, v209, v101
	v_exp_f32_e32 v190, v126
	v_exp_f32_e32 v191, v127
	v_exp_f32_e32 v192, v128
	v_exp_f32_e32 v193, v129
	v_exp_f32_e32 v194, v122
	v_exp_f32_e32 v195, v123
	v_exp_f32_e32 v196, v124
	v_exp_f32_e32 v197, v125
	v_add_u32_e32 v228, s12, v168
	v_mad_i64_i32 v[228:229], s[0:1], v228, s63, v[224:225]
	v_add_f32_e32 v190, 1.0, v190
	v_add_f32_e32 v191, 1.0, v191
	v_add_f32_e32 v192, 1.0, v192
	v_add_f32_e32 v193, 1.0, v193
	v_add_f32_e32 v194, 1.0, v194
	v_add_f32_e32 v195, 1.0, v195
	v_add_f32_e32 v196, 1.0, v196
	v_add_f32_e32 v197, 1.0, v197
	v_rcp_f32_e32 v190, v190
	v_rcp_f32_e32 v191, v191
	v_rcp_f32_e32 v192, v192
	v_rcp_f32_e32 v193, v193
	v_rcp_f32_e32 v194, v194
	v_rcp_f32_e32 v195, v195
	v_rcp_f32_e32 v196, v196
	v_rcp_f32_e32 v197, v197
	v_mul_f32_e32 v126, v126, v190
	v_mul_f32_e32 v127, v127, v191
	v_mul_f32_e32 v128, v128, v192
	v_mul_f32_e32 v129, v129, v193
	v_mul_f32_e32 v122, v122, v194
	v_mul_f32_e32 v123, v123, v195
	v_mul_f32_e32 v124, v124, v196
	v_mul_f32_e32 v125, v125, v197
	v_mul_f32_e32 v126, v118, v126
	v_mul_f32_e32 v127, v119, v127
	v_mul_f32_e32 v128, v120, v128
	v_mul_f32_e32 v129, v121, v129
	v_mul_f32_e32 v122, v114, v122
	v_mul_f32_e32 v123, v115, v123
	v_mul_f32_e32 v124, v116, v124
	v_mul_f32_e32 v125, v117, v125
	v_cvt_pk_bf16_f32 v202, v126, v127
	v_cvt_pk_bf16_f32 v203, v128, v129
	v_cvt_pk_bf16_f32 v204, v122, v123
	v_cvt_pk_bf16_f32 v205, v124, v125
	global_store_dwordx4 v[228:229], v[202:205], off
	v_mul_f32_e32 v211, 0xbf317218, v210
	v_mul_f32_e32 v210, 0xbfb8aa3b, v210
	v_fma_f32 v94, v94, v210, v110
	v_fma_f32 v95, v95, v210, v111
	v_fma_f32 v96, v96, v210, v112
	v_fma_f32 v97, v97, v210, v113
	v_fma_f32 v90, v90, v210, v106
	v_fma_f32 v91, v91, v210, v107
	v_fma_f32 v92, v92, v210, v108
	v_fma_f32 v93, v93, v210, v109
	v_fma_f32 v86, v86, v211, v102
	v_fma_f32 v87, v87, v211, v103
	v_fma_f32 v88, v88, v211, v104
	v_fma_f32 v89, v89, v211, v105
	v_fma_f32 v82, v82, v211, v98
	v_fma_f32 v83, v83, v211, v99
	v_fma_f32 v84, v84, v211, v100
	v_fma_f32 v85, v85, v211, v101
	v_exp_f32_e32 v190, v94
	v_exp_f32_e32 v191, v95
	v_exp_f32_e32 v192, v96
	v_exp_f32_e32 v193, v97
	v_exp_f32_e32 v194, v90
	v_exp_f32_e32 v195, v91
	v_exp_f32_e32 v196, v92
	v_exp_f32_e32 v197, v93
	v_add_u32_e32 v226, s12, v169
	v_mad_i64_i32 v[226:227], s[0:1], v226, s63, v[224:225]
	v_add_f32_e32 v190, 1.0, v190
	v_add_f32_e32 v191, 1.0, v191
	v_add_f32_e32 v192, 1.0, v192
	v_add_f32_e32 v193, 1.0, v193
	v_add_f32_e32 v194, 1.0, v194
	v_add_f32_e32 v195, 1.0, v195
	v_add_f32_e32 v196, 1.0, v196
	v_add_f32_e32 v197, 1.0, v197
	v_rcp_f32_e32 v190, v190
	v_rcp_f32_e32 v191, v191
	v_rcp_f32_e32 v192, v192
	v_rcp_f32_e32 v193, v193
	v_rcp_f32_e32 v194, v194
	v_rcp_f32_e32 v195, v195
	v_rcp_f32_e32 v196, v196
	v_rcp_f32_e32 v197, v197
	v_mul_f32_e32 v94, v94, v190
	v_mul_f32_e32 v95, v95, v191
	v_mul_f32_e32 v96, v96, v192
	v_mul_f32_e32 v97, v97, v193
	v_mul_f32_e32 v90, v90, v194
	v_mul_f32_e32 v91, v91, v195
	v_mul_f32_e32 v92, v92, v196
	v_mul_f32_e32 v93, v93, v197
	v_mul_f32_e32 v94, v86, v94
	v_mul_f32_e32 v95, v87, v95
	v_mul_f32_e32 v96, v88, v96
	v_mul_f32_e32 v97, v89, v97
	v_mul_f32_e32 v90, v82, v90
	v_mul_f32_e32 v91, v83, v91
	v_mul_f32_e32 v92, v84, v92
	v_mul_f32_e32 v93, v85, v93
	v_cvt_pk_bf16_f32 v198, v94, v95
	v_cvt_pk_bf16_f32 v199, v96, v97
	v_cvt_pk_bf16_f32 v200, v90, v91
	v_cvt_pk_bf16_f32 v201, v92, v93
	global_store_dwordx4 v[226:227], v[198:201], off
	v_mul_f32_e32 v213, 0xbf317218, v212
	v_mul_f32_e32 v212, 0xbfb8aa3b, v212
	v_fma_f32 v78, v78, v212, v110
	v_fma_f32 v79, v79, v212, v111
	v_fma_f32 v80, v80, v212, v112
	v_fma_f32 v81, v81, v212, v113
	v_fma_f32 v74, v74, v212, v106
	v_fma_f32 v75, v75, v212, v107
	v_fma_f32 v76, v76, v212, v108
	v_fma_f32 v77, v77, v212, v109
	v_fma_f32 v70, v70, v213, v102
	v_fma_f32 v71, v71, v213, v103
	v_fma_f32 v72, v72, v213, v104
	v_fma_f32 v73, v73, v213, v105
	v_fma_f32 v66, v66, v213, v98
	v_fma_f32 v67, v67, v213, v99
	v_fma_f32 v68, v68, v213, v100
	v_fma_f32 v69, v69, v213, v101
	v_exp_f32_e32 v190, v78
	v_exp_f32_e32 v191, v79
	v_exp_f32_e32 v192, v80
	v_exp_f32_e32 v193, v81
	v_exp_f32_e32 v194, v74
	v_exp_f32_e32 v195, v75
	v_exp_f32_e32 v196, v76
	v_exp_f32_e32 v197, v77
	v_add_u32_e32 v228, s12, v170
	v_mad_i64_i32 v[228:229], s[0:1], v228, s63, v[224:225]
	v_add_f32_e32 v190, 1.0, v190
	v_add_f32_e32 v191, 1.0, v191
	v_add_f32_e32 v192, 1.0, v192
	v_add_f32_e32 v193, 1.0, v193
	v_add_f32_e32 v194, 1.0, v194
	v_add_f32_e32 v195, 1.0, v195
	v_add_f32_e32 v196, 1.0, v196
	v_add_f32_e32 v197, 1.0, v197
	v_rcp_f32_e32 v190, v190
	v_rcp_f32_e32 v191, v191
	v_rcp_f32_e32 v192, v192
	v_rcp_f32_e32 v193, v193
	v_rcp_f32_e32 v194, v194
	v_rcp_f32_e32 v195, v195
	v_rcp_f32_e32 v196, v196
	v_rcp_f32_e32 v197, v197
	v_mul_f32_e32 v78, v78, v190
	v_mul_f32_e32 v79, v79, v191
	v_mul_f32_e32 v80, v80, v192
	v_mul_f32_e32 v81, v81, v193
	v_mul_f32_e32 v74, v74, v194
	v_mul_f32_e32 v75, v75, v195
	v_mul_f32_e32 v76, v76, v196
	v_mul_f32_e32 v77, v77, v197
	v_mul_f32_e32 v78, v70, v78
	v_mul_f32_e32 v79, v71, v79
	v_mul_f32_e32 v80, v72, v80
	v_mul_f32_e32 v81, v73, v81
	v_mul_f32_e32 v74, v66, v74
	v_mul_f32_e32 v75, v67, v75
	v_mul_f32_e32 v76, v68, v76
	v_mul_f32_e32 v77, v69, v77
	v_cvt_pk_bf16_f32 v202, v78, v79
	v_cvt_pk_bf16_f32 v203, v80, v81
	v_cvt_pk_bf16_f32 v204, v74, v75
	v_cvt_pk_bf16_f32 v205, v76, v77
	global_store_dwordx4 v[228:229], v[202:205], off
	v_mul_f32_e32 v215, 0xbf317218, v214
	v_mul_f32_e32 v214, 0xbfb8aa3b, v214
	v_fma_f32 v62, v62, v214, v110
	v_fma_f32 v63, v63, v214, v111
	v_fma_f32 v64, v64, v214, v112
	v_fma_f32 v65, v65, v214, v113
	v_fma_f32 v58, v58, v214, v106
	v_fma_f32 v59, v59, v214, v107
	v_fma_f32 v60, v60, v214, v108
	v_fma_f32 v61, v61, v214, v109
	v_fma_f32 v54, v54, v215, v102
	v_fma_f32 v55, v55, v215, v103
	v_fma_f32 v56, v56, v215, v104
	v_fma_f32 v57, v57, v215, v105
	v_fma_f32 v50, v50, v215, v98
	v_fma_f32 v51, v51, v215, v99
	v_fma_f32 v52, v52, v215, v100
	v_fma_f32 v53, v53, v215, v101
	v_exp_f32_e32 v190, v62
	v_exp_f32_e32 v191, v63
	v_exp_f32_e32 v192, v64
	v_exp_f32_e32 v193, v65
	v_exp_f32_e32 v194, v58
	v_exp_f32_e32 v195, v59
	v_exp_f32_e32 v196, v60
	v_exp_f32_e32 v197, v61
	v_add_u32_e32 v226, s12, v171
	v_mad_i64_i32 v[226:227], s[0:1], v226, s63, v[224:225]
	v_add_f32_e32 v190, 1.0, v190
	v_add_f32_e32 v191, 1.0, v191
	v_add_f32_e32 v192, 1.0, v192
	v_add_f32_e32 v193, 1.0, v193
	v_add_f32_e32 v194, 1.0, v194
	v_add_f32_e32 v195, 1.0, v195
	v_add_f32_e32 v196, 1.0, v196
	v_add_f32_e32 v197, 1.0, v197
	v_rcp_f32_e32 v190, v190
	v_rcp_f32_e32 v191, v191
	v_rcp_f32_e32 v192, v192
	v_rcp_f32_e32 v193, v193
	v_rcp_f32_e32 v194, v194
	v_rcp_f32_e32 v195, v195
	v_rcp_f32_e32 v196, v196
	v_rcp_f32_e32 v197, v197
	v_mul_f32_e32 v62, v62, v190
	v_mul_f32_e32 v63, v63, v191
	v_mul_f32_e32 v64, v64, v192
	v_mul_f32_e32 v65, v65, v193
	v_mul_f32_e32 v58, v58, v194
	v_mul_f32_e32 v59, v59, v195
	v_mul_f32_e32 v60, v60, v196
	v_mul_f32_e32 v61, v61, v197
	v_mul_f32_e32 v62, v54, v62
	v_mul_f32_e32 v63, v55, v63
	v_mul_f32_e32 v64, v56, v64
	v_mul_f32_e32 v65, v57, v65
	v_mul_f32_e32 v58, v50, v58
	v_mul_f32_e32 v59, v51, v59
	v_mul_f32_e32 v60, v52, v60
	v_mul_f32_e32 v61, v53, v61
	v_cvt_pk_bf16_f32 v198, v62, v63
	v_cvt_pk_bf16_f32 v199, v64, v65
	v_cvt_pk_bf16_f32 v200, v58, v59
	v_cvt_pk_bf16_f32 v201, v60, v61
	global_store_dwordx4 v[226:227], v[198:201], off
	v_mul_f32_e32 v217, 0xbf317218, v216
	v_mul_f32_e32 v216, 0xbfb8aa3b, v216
	v_fma_f32 v46, v46, v216, v110
	v_fma_f32 v47, v47, v216, v111
	v_fma_f32 v48, v48, v216, v112
	v_fma_f32 v49, v49, v216, v113
	v_fma_f32 v42, v42, v216, v106
	v_fma_f32 v43, v43, v216, v107
	v_fma_f32 v44, v44, v216, v108
	v_fma_f32 v45, v45, v216, v109
	v_fma_f32 v38, v38, v217, v102
	v_fma_f32 v39, v39, v217, v103
	v_fma_f32 v40, v40, v217, v104
	v_fma_f32 v41, v41, v217, v105
	v_fma_f32 v34, v34, v217, v98
	v_fma_f32 v35, v35, v217, v99
	v_fma_f32 v36, v36, v217, v100
	v_fma_f32 v37, v37, v217, v101
	v_exp_f32_e32 v190, v46
	v_exp_f32_e32 v191, v47
	v_exp_f32_e32 v192, v48
	v_exp_f32_e32 v193, v49
	v_exp_f32_e32 v194, v42
	v_exp_f32_e32 v195, v43
	v_exp_f32_e32 v196, v44
	v_exp_f32_e32 v197, v45
	v_add_u32_e32 v228, s12, v172
	v_mad_i64_i32 v[228:229], s[0:1], v228, s63, v[224:225]
	v_add_f32_e32 v190, 1.0, v190
	v_add_f32_e32 v191, 1.0, v191
	v_add_f32_e32 v192, 1.0, v192
	v_add_f32_e32 v193, 1.0, v193
	v_add_f32_e32 v194, 1.0, v194
	v_add_f32_e32 v195, 1.0, v195
	v_add_f32_e32 v196, 1.0, v196
	v_add_f32_e32 v197, 1.0, v197
	v_rcp_f32_e32 v190, v190
	v_rcp_f32_e32 v191, v191
	v_rcp_f32_e32 v192, v192
	v_rcp_f32_e32 v193, v193
	v_rcp_f32_e32 v194, v194
	v_rcp_f32_e32 v195, v195
	v_rcp_f32_e32 v196, v196
	v_rcp_f32_e32 v197, v197
	v_mul_f32_e32 v46, v46, v190
	v_mul_f32_e32 v47, v47, v191
	v_mul_f32_e32 v48, v48, v192
	v_mul_f32_e32 v49, v49, v193
	v_mul_f32_e32 v42, v42, v194
	v_mul_f32_e32 v43, v43, v195
	v_mul_f32_e32 v44, v44, v196
	v_mul_f32_e32 v45, v45, v197
	v_mul_f32_e32 v46, v38, v46
	v_mul_f32_e32 v47, v39, v47
	v_mul_f32_e32 v48, v40, v48
	v_mul_f32_e32 v49, v41, v49
	v_mul_f32_e32 v42, v34, v42
	v_mul_f32_e32 v43, v35, v43
	v_mul_f32_e32 v44, v36, v44
	v_mul_f32_e32 v45, v37, v45
	v_cvt_pk_bf16_f32 v202, v46, v47
	v_cvt_pk_bf16_f32 v203, v48, v49
	v_cvt_pk_bf16_f32 v204, v42, v43
	v_cvt_pk_bf16_f32 v205, v44, v45
	global_store_dwordx4 v[228:229], v[202:205], off
	v_mul_f32_e32 v219, 0xbf317218, v218
	v_mul_f32_e32 v218, 0xbfb8aa3b, v218
	v_fma_f32 v30, v30, v218, v110
	v_fma_f32 v31, v31, v218, v111
	v_fma_f32 v32, v32, v218, v112
	v_fma_f32 v33, v33, v218, v113
	v_fma_f32 v26, v26, v218, v106
	v_fma_f32 v27, v27, v218, v107
	v_fma_f32 v28, v28, v218, v108
	v_fma_f32 v29, v29, v218, v109
	v_fma_f32 v22, v22, v219, v102
	v_fma_f32 v23, v23, v219, v103
	v_fma_f32 v24, v24, v219, v104
	v_fma_f32 v25, v25, v219, v105
	v_fma_f32 v18, v18, v219, v98
	v_fma_f32 v19, v19, v219, v99
	v_fma_f32 v20, v20, v219, v100
	v_fma_f32 v21, v21, v219, v101
	v_exp_f32_e32 v190, v30
	v_exp_f32_e32 v191, v31
	v_exp_f32_e32 v192, v32
	v_exp_f32_e32 v193, v33
	v_exp_f32_e32 v194, v26
	v_exp_f32_e32 v195, v27
	v_exp_f32_e32 v196, v28
	v_exp_f32_e32 v197, v29
	v_add_u32_e32 v226, s12, v173
	v_mad_i64_i32 v[226:227], s[0:1], v226, s63, v[224:225]
	v_add_f32_e32 v190, 1.0, v190
	v_add_f32_e32 v191, 1.0, v191
	v_add_f32_e32 v192, 1.0, v192
	v_add_f32_e32 v193, 1.0, v193
	v_add_f32_e32 v194, 1.0, v194
	v_add_f32_e32 v195, 1.0, v195
	v_add_f32_e32 v196, 1.0, v196
	v_add_f32_e32 v197, 1.0, v197
	v_rcp_f32_e32 v190, v190
	v_rcp_f32_e32 v191, v191
	v_rcp_f32_e32 v192, v192
	v_rcp_f32_e32 v193, v193
	v_rcp_f32_e32 v194, v194
	v_rcp_f32_e32 v195, v195
	v_rcp_f32_e32 v196, v196
	v_rcp_f32_e32 v197, v197
	v_mul_f32_e32 v30, v30, v190
	v_mul_f32_e32 v31, v31, v191
	v_mul_f32_e32 v32, v32, v192
	v_mul_f32_e32 v33, v33, v193
	v_mul_f32_e32 v26, v26, v194
	v_mul_f32_e32 v27, v27, v195
	v_mul_f32_e32 v28, v28, v196
	v_mul_f32_e32 v29, v29, v197
	v_mul_f32_e32 v30, v22, v30
	v_mul_f32_e32 v31, v23, v31
	v_mul_f32_e32 v32, v24, v32
	v_mul_f32_e32 v33, v25, v33
	v_mul_f32_e32 v26, v18, v26
	v_mul_f32_e32 v27, v19, v27
	v_mul_f32_e32 v28, v20, v28
	v_mul_f32_e32 v29, v21, v29
	v_cvt_pk_bf16_f32 v198, v30, v31
	v_cvt_pk_bf16_f32 v199, v32, v33
	v_cvt_pk_bf16_f32 v200, v26, v27
	v_cvt_pk_bf16_f32 v201, v28, v29
	global_store_dwordx4 v[226:227], v[198:201], off
	v_mul_f32_e32 v221, 0xbf317218, v220
	v_mul_f32_e32 v220, 0xbfb8aa3b, v220
	v_fma_f32 v14, v14, v220, v110
	v_fma_f32 v15, v15, v220, v111
	v_fma_f32 v16, v16, v220, v112
	v_fma_f32 v17, v17, v220, v113
	v_fma_f32 v10, v10, v220, v106
	v_fma_f32 v11, v11, v220, v107
	v_fma_f32 v12, v12, v220, v108
	v_fma_f32 v13, v13, v220, v109
	v_fma_f32 v6, v6, v221, v102
	v_fma_f32 v7, v7, v221, v103
	v_fma_f32 v8, v8, v221, v104
	v_fma_f32 v9, v9, v221, v105
	v_fma_f32 v2, v2, v221, v98
	v_fma_f32 v3, v3, v221, v99
	v_fma_f32 v4, v4, v221, v100
	v_fma_f32 v5, v5, v221, v101
	v_exp_f32_e32 v190, v14
	v_exp_f32_e32 v191, v15
	v_exp_f32_e32 v192, v16
	v_exp_f32_e32 v193, v17
	v_exp_f32_e32 v194, v10
	v_exp_f32_e32 v195, v11
	v_exp_f32_e32 v196, v12
	v_exp_f32_e32 v197, v13
	v_add_u32_e32 v228, s12, v174
	v_mad_i64_i32 v[228:229], s[0:1], v228, s63, v[224:225]
	v_add_f32_e32 v190, 1.0, v190
	v_add_f32_e32 v191, 1.0, v191
	v_add_f32_e32 v192, 1.0, v192
	v_add_f32_e32 v193, 1.0, v193
	v_add_f32_e32 v194, 1.0, v194
	v_add_f32_e32 v195, 1.0, v195
	v_add_f32_e32 v196, 1.0, v196
	v_add_f32_e32 v197, 1.0, v197
	v_rcp_f32_e32 v190, v190
	v_rcp_f32_e32 v191, v191
	v_rcp_f32_e32 v192, v192
	v_rcp_f32_e32 v193, v193
	v_rcp_f32_e32 v194, v194
	v_rcp_f32_e32 v195, v195
	v_rcp_f32_e32 v196, v196
	v_rcp_f32_e32 v197, v197
	v_mul_f32_e32 v14, v14, v190
	v_mul_f32_e32 v15, v15, v191
	v_mul_f32_e32 v16, v16, v192
	v_mul_f32_e32 v17, v17, v193
	v_mul_f32_e32 v10, v10, v194
	v_mul_f32_e32 v11, v11, v195
	v_mul_f32_e32 v12, v12, v196
	v_mul_f32_e32 v13, v13, v197
	v_mul_f32_e32 v14, v6, v14
	v_mul_f32_e32 v15, v7, v15
	v_mul_f32_e32 v16, v8, v16
	v_mul_f32_e32 v17, v9, v17
	v_mul_f32_e32 v10, v2, v10
	v_mul_f32_e32 v11, v3, v11
	v_mul_f32_e32 v12, v4, v12
	v_mul_f32_e32 v13, v5, v13
	v_cvt_pk_bf16_f32 v202, v14, v15
	v_cvt_pk_bf16_f32 v203, v16, v17
	v_cvt_pk_bf16_f32 v204, v10, v11
	v_cvt_pk_bf16_f32 v205, v12, v13
	global_store_dwordx4 v[228:229], v[202:205], off
	s_andn2_b64 vcc, exec, s[4:5]
	s_mov_b64 s[0:1], -1
	s_cbranch_vccnz .LBB0_1471
	s_andn2_b64 vcc, exec, s[8:9]
	s_cbranch_vccnz .LBB0_1470
	s_barrier
	s_branch .LBB0_1470
